# grid barrier: the round's last cross-XCC arriver releases every XCC generation word directly; XCC leaders wait on their own XCC word (one release hop less per barrier)
# speedup vs baseline: 1.0272x; 1.0056x over previous
; __device__ __forceinline__ unsigned xb_ld(unsigned* p)              { return __hip_atomic_load(p, __ATOMIC_RELAXED, __HIP_MEMORY_SCOPE_AGENT); }
; __device__ __forceinline__ unsigned xb_add(unsigned* p, unsigned v) { return __hip_atomic_fetch_add(p, v, __ATOMIC_RELAXED, __HIP_MEMORY_SCOPE_AGENT); }
; #define XB_SPIN(cond, bar) do { unsigned _sp = 0; while (cond) { __builtin_amdgcn_s_sleep(1); \
;     if ((++_sp & 255u) == 0u) { if (xb_ld(&(bar)[XB_TMO])) break; if (_sp > XB_SPIN_CAP) { atomicAdd(&(bar)[XB_TMO], 1u); break; } } } } while (0)
; __device__ __forceinline__ void xcd_barrier(const XcdBarrier& b, const int tid) {
;     ...
;         const unsigned old = xb_add(&bar[XB_XSUB(b.x)], 1u);
;         const unsigned gen = old / nloc;
;         if (old + 1u == (gen + 1u) * nloc) {
;             __builtin_amdgcn_fence(__ATOMIC_RELEASE, "agent");
;             asm volatile("s_waitcnt vmcnt(0)" ::: "memory");
;             const unsigned og = xb_add(&bar[XB_TOP], 1u);
;             const unsigned tg = og / nx;
;             if (og + 1u == (tg + 1u) * nx) xb_add(&bar[XB_TOPGEN], 1u);
;             else XB_SPIN(xb_ld(&bar[XB_TOPGEN]) == tg, bar);
;             __builtin_amdgcn_fence(__ATOMIC_ACQUIRE, "agent");
;             xb_add(&bar[XB_XGEN(b.x)], 1u);
;             asm volatile("s_waitcnt vmcnt(0)" ::: "memory");
;         } else {
;             XB_SPIN(xb_ld(&bar[XB_XGEN(b.x)]) == gen, bar);
.LBB0_588:
	s_or_b64 exec, exec, s[2:3]
	v_cvt_f32_u32_e32 v5, v3
	s_waitcnt vmcnt(0)
	v_readfirstlane_b32 s2, v4
	v_sub_u32_e32 v4, 0, v3
	v_rcp_iflag_f32_e32 v5, v5
	v_add_u32_e32 v6, s2, v0
	v_mul_f32_e32 v5, 0x4f7ffffe, v5
	v_cvt_u32_f32_e32 v5, v5
	v_mul_lo_u32 v0, v4, v5
	v_mul_hi_u32 v0, v5, v0
	v_add_u32_e32 v0, v5, v0
	v_mul_hi_u32 v0, v6, v0
	v_mul_lo_u32 v4, v0, v3
	v_sub_u32_e32 v4, v6, v4
	v_add_u32_e32 v5, 1, v0
	v_cmp_ge_u32_e32 vcc, v4, v3
	s_nop 1
	v_cndmask_b32_e32 v0, v0, v5, vcc
	v_sub_u32_e32 v5, v4, v3
	v_cndmask_b32_e32 v4, v4, v5, vcc
	v_add_u32_e32 v5, 1, v0
	v_cmp_ge_u32_e32 vcc, v4, v3
	v_add_u32_e32 v4, 1, v6
	s_nop 0
	v_cndmask_b32_e32 v0, v0, v5, vcc
	v_mul_lo_u32 v5, v3, v0
	v_add_u32_e32 v3, v5, v3
	v_cmp_ne_u32_e32 vcc, v4, v3
	v_readfirstlane_b32 s98, v0
	s_and_saveexec_b64 s[2:3], vcc
	s_xor_b64 s[2:3], exec, s[2:3]
	s_cbranch_execz .LBB0_602
	v_readlane_b32 s4, v250, 11
	v_readlane_b32 s5, v250, 12
	s_waitcnt lgkmcnt(0)
	s_nop 3
	global_load_dword v2, v1, s[4:5] sc1
	s_waitcnt vmcnt(0)
	v_cmp_eq_u32_e32 vcc, v2, v0
	s_and_saveexec_b64 s[4:5], vcc
	s_cbranch_execz .LBB0_601
	s_mov_b32 s20, 1
	s_mov_b64 s[6:7], 0
	s_branch .LBB0_592

; __device__ __forceinline__ unsigned xb_ld(unsigned* p)              { return __hip_atomic_load(p, __ATOMIC_RELAXED, __HIP_MEMORY_SCOPE_AGENT); }
; __device__ __forceinline__ unsigned xb_add(unsigned* p, unsigned v) { return __hip_atomic_fetch_add(p, v, __ATOMIC_RELAXED, __HIP_MEMORY_SCOPE_AGENT); }
; #define XB_SPIN(cond, bar) do { unsigned _sp = 0; while (cond) { __builtin_amdgcn_s_sleep(1); \
;     if ((++_sp & 255u) == 0u) { if (xb_ld(&(bar)[XB_TMO])) break; if (_sp > XB_SPIN_CAP) { atomicAdd(&(bar)[XB_TMO], 1u); break; } } } } while (0)
; __device__ __forceinline__ void xcd_barrier(const XcdBarrier& b, const int tid) {
;     ...
;             const unsigned og = xb_add(&bar[XB_TOP], 1u);
;             const unsigned tg = og / nx;
;             if (og + 1u == (tg + 1u) * nx) xb_add(&bar[XB_TOPGEN], 1u);
;             else XB_SPIN(xb_ld(&bar[XB_TOPGEN]) == tg, bar);
;             __builtin_amdgcn_fence(__ATOMIC_ACQUIRE, "agent");
;             xb_add(&bar[XB_XGEN(b.x)], 1u);
;             asm volatile("s_waitcnt vmcnt(0)" ::: "memory");
;         } else {
;             XB_SPIN(xb_ld(&bar[XB_XGEN(b.x)]) == gen, bar);
.LBB0_605:
	s_or_b64 exec, exec, s[4:5]
	s_waitcnt vmcnt(0)
	v_readfirstlane_b32 s2, v3
	v_sub_u32_e32 v4, 0, v2
	s_mov_b64 s[4:5], -1
	v_add_u32_e32 v3, s2, v0
	v_cvt_f32_u32_e32 v0, v2
	v_readlane_b32 s2, v250, 15
	v_readlane_b32 s3, v250, 16
	v_rcp_iflag_f32_e32 v0, v0
	s_nop 0
	v_mul_f32_e32 v0, 0x4f7ffffe, v0
	v_cvt_u32_f32_e32 v0, v0
	v_mul_lo_u32 v4, v4, v0
	v_mul_hi_u32 v4, v0, v4
	v_add_u32_e32 v0, v0, v4
	v_mul_hi_u32 v0, v3, v0
	v_mul_lo_u32 v4, v0, v2
	v_sub_u32_e32 v4, v3, v4
	v_cmp_ge_u32_e32 vcc, v4, v2
	v_add_u32_e32 v5, 1, v0
	v_add_u32_e32 v3, 1, v3
	v_cndmask_b32_e32 v0, v0, v5, vcc
	v_sub_u32_e32 v5, v4, v2
	v_cndmask_b32_e32 v4, v4, v5, vcc
	v_cmp_ge_u32_e32 vcc, v4, v2
	v_add_u32_e32 v4, 1, v0
	s_nop 0
	v_cndmask_b32_e32 v0, v0, v4, vcc
	v_mul_lo_u32 v4, v2, v0
	v_add_u32_e32 v2, v4, v2
	v_cmp_ne_u32_e32 vcc, v3, v2
	v_mov_b32_e32 v0, s98
	v_mov_b64_e32 v[2:3], s[2:3]
	s_and_saveexec_b64 s[2:3], vcc
	s_cbranch_execnz .Lxb_notlast
	s_mov_b64 exec, s[2:3]
	v_readlane_b32 s4, v250, 7
	v_readlane_b32 s5, v250, 8
	v_mov_b32_e32 v4, 1
	s_add_u32 s4, s4, 0x2200
	s_addc_u32 s5, s5, 0
	global_atomic_add v1, v4, s[4:5]
	global_atomic_add v1, v4, s[4:5] offset:256
	global_atomic_add v1, v4, s[4:5] offset:512
	global_atomic_add v1, v4, s[4:5] offset:768
	global_atomic_add v1, v4, s[4:5] offset:1024
	global_atomic_add v1, v4, s[4:5] offset:1280
	global_atomic_add v1, v4, s[4:5] offset:1536
	global_atomic_add v1, v4, s[4:5] offset:1792
	global_atomic_add v1, v4, s[4:5] offset:2048
	global_atomic_add v1, v4, s[4:5] offset:2304
	global_atomic_add v1, v4, s[4:5] offset:2560
	global_atomic_add v1, v4, s[4:5] offset:2816
	global_atomic_add v1, v4, s[4:5] offset:3072
	global_atomic_add v1, v4, s[4:5] offset:3328
	global_atomic_add v1, v4, s[4:5] offset:3584
	global_atomic_add v1, v4, s[4:5] offset:3840
	s_mov_b64 s[4:5], 0
	s_branch .LBB0_617
.Lxb_notlast:
	v_readlane_b32 s4, v250, 11
	v_readlane_b32 s5, v250, 12
	s_mov_b64 s[6:7], 0
	s_nop 3
	global_load_dword v2, v1, s[4:5] sc1
	s_waitcnt vmcnt(0)
	v_cmp_eq_u32_e32 vcc, v2, v0
	s_and_saveexec_b64 s[4:5], vcc
	s_cbranch_execz .LBB0_616
	s_mov_b32 s20, 1
	s_branch .LBB0_609

; __device__ __forceinline__ unsigned xb_add(unsigned* p, unsigned v) { return __hip_atomic_fetch_add(p, v, __ATOMIC_RELAXED, __HIP_MEMORY_SCOPE_AGENT); }
; __device__ __forceinline__ void xcd_barrier(const XcdBarrier& b, const int tid) {
;     ...
;             __builtin_amdgcn_fence(__ATOMIC_ACQUIRE, "agent");
;             xb_add(&bar[XB_XGEN(b.x)], 1u);
;             asm volatile("s_waitcnt vmcnt(0)" ::: "memory");
.LBB0_619:
	s_or_b64 exec, exec, s[2:3]
	s_mov_b64 s[2:3], exec
	v_mbcnt_lo_u32_b32 v0, s2, 0
	v_mbcnt_hi_u32_b32 v0, s3, v0
	v_cmp_eq_u32_e32 vcc, 0, v0
	s_waitcnt vmcnt(0)
	buffer_inv sc1
	s_and_saveexec_b64 s[4:5], vcc
	s_cbranch_execz .LBB0_621
	s_bcnt1_i32_b64 s2, s[2:3]
	v_mov_b32_e32 v0, s2
	v_readlane_b32 s2, v250, 11
	v_readlane_b32 s3, v250, 12
	s_nop 4
	s_nop 0

; #define LAS __attribute__((address_space(3)))
; __global__ void __launch_bounds__(512, 2) fwd_kernel(Args a) {
;     extern __shared__ __attribute__((aligned(16))) unsigned char lds_raw[];
;     LAS unsigned char* lds = (LAS unsigned char*)lds_raw;
;     cg::grid_group grid = cg::this_grid();
;     volatile LAS unsigned* bst = (volatile LAS unsigned*)(lds + LDS_BYTES - 64);
;     const int wid_s = __builtin_amdgcn_readfirstlane((int)threadIdx.x >> 6);
	.amdhsa_kernel _Z10fwd_kernel4Args
		.amdhsa_group_segment_fixed_size 0
		.amdhsa_private_segment_fixed_size 0
		.amdhsa_kernarg_size 416
		.amdhsa_user_sgpr_count 2
		.amdhsa_user_sgpr_dispatch_ptr 0
		.amdhsa_user_sgpr_queue_ptr 0
		.amdhsa_user_sgpr_kernarg_segment_ptr 1
		.amdhsa_user_sgpr_dispatch_id 0
		.amdhsa_user_sgpr_kernarg_preload_length 0
		.amdhsa_user_sgpr_kernarg_preload_offset 0
		.amdhsa_user_sgpr_private_segment_size 0
		.amdhsa_uses_dynamic_stack 0
		.amdhsa_enable_private_segment 0
		.amdhsa_system_sgpr_workgroup_id_x 1
		.amdhsa_system_sgpr_workgroup_id_y 0
		.amdhsa_system_sgpr_workgroup_id_z 0
		.amdhsa_system_sgpr_workgroup_info 0
		.amdhsa_system_vgpr_workitem_id 2
		.amdhsa_next_free_vgpr 256
		.amdhsa_next_free_sgpr 100
		.amdhsa_accum_offset 256
		.amdhsa_reserve_vcc 1
		.amdhsa_float_round_mode_32 0
		.amdhsa_float_round_mode_16_64 0
		.amdhsa_float_denorm_mode_32 3
		.amdhsa_float_denorm_mode_16_64 3
		.amdhsa_dx10_clamp 1
		.amdhsa_ieee_mode 1
		.amdhsa_fp16_overflow 0
		.amdhsa_tg_split 0
		.amdhsa_exception_fp_ieee_invalid_op 0
		.amdhsa_exception_fp_denorm_src 0
		.amdhsa_exception_fp_ieee_div_zero 0
		.amdhsa_exception_fp_ieee_overflow 0
		.amdhsa_exception_fp_ieee_underflow 0
		.amdhsa_exception_fp_ieee_inexact 0
		.amdhsa_exception_int_div_zero 0
	.end_amdhsa_kernel

; __global__ void __launch_bounds__(512, 2) fwd_kernel(Args a) {
;     extern __shared__ __attribute__((aligned(16))) unsigned char lds_raw[];
.Lfunc_end0:
	.size	_Z10fwd_kernel4Args, .Lfunc_end0-_Z10fwd_kernel4Args
	.set _Z10fwd_kernel4Args.num_vgpr, 256
	.set _Z10fwd_kernel4Args.num_agpr, 0
	.set _Z10fwd_kernel4Args.numbered_sgpr, 100
	.set _Z10fwd_kernel4Args.num_named_barrier, 0
	.set _Z10fwd_kernel4Args.private_seg_size, 0
	.set _Z10fwd_kernel4Args.uses_vcc, 1
	.set _Z10fwd_kernel4Args.uses_flat_scratch, 0
	.set _Z10fwd_kernel4Args.has_dyn_sized_stack, 0
	.set _Z10fwd_kernel4Args.has_recursion, 0
	.set _Z10fwd_kernel4Args.has_indirect_call, 0

; __global__ void __launch_bounds__(512, 2) fwd_kernel(Args a) {
;     extern __shared__ __attribute__((aligned(16))) unsigned char lds_raw[];
amdhsa.kernels:
  - .agpr_count:     0
    .args:
      - .offset:         0
        .size:           160
        .value_kind:     by_value
      - .offset:         160
        .size:           4
        .value_kind:     hidden_block_count_x
      - .offset:         164
        .size:           4
        .value_kind:     hidden_block_count_y
      - .offset:         168
        .size:           4
        .value_kind:     hidden_block_count_z
      - .offset:         172
        .size:           2
        .value_kind:     hidden_group_size_x
      - .offset:         174
        .size:           2
        .value_kind:     hidden_group_size_y
      - .offset:         176
        .size:           2
        .value_kind:     hidden_group_size_z
      - .offset:         178
        .size:           2
        .value_kind:     hidden_remainder_x
      - .offset:         180
        .size:           2
        .value_kind:     hidden_remainder_y
      - .offset:         182
        .size:           2
        .value_kind:     hidden_remainder_z
      - .offset:         200
        .size:           8
        .value_kind:     hidden_global_offset_x
      - .offset:         208
        .size:           8
        .value_kind:     hidden_global_offset_y
      - .offset:         216
        .size:           8
        .value_kind:     hidden_global_offset_z
      - .offset:         224
        .size:           2
        .value_kind:     hidden_grid_dims
      - .offset:         248
        .size:           8
        .value_kind:     hidden_multigrid_sync_arg
      - .offset:         280
        .size:           4
        .value_kind:     hidden_dynamic_lds_size
    .group_segment_fixed_size: 0
    .kernarg_segment_align: 8
    .kernarg_segment_size: 416
    .language:       OpenCL C
    .language_version:
      - 2
      - 0
    .max_flat_workgroup_size: 512
    .name:           _Z10fwd_kernel4Args
    .private_segment_fixed_size: 0
    .sgpr_count:     106
    .sgpr_spill_count: 407
    .symbol:         _Z10fwd_kernel4Args.kd
    .uniform_work_group_size: 1
    .uses_dynamic_stack: false
    .vgpr_count:     256
    .vgpr_spill_count: 0
    .wavefront_size: 64
